# r55 layout variant: GDN-scan chunk loop code shifted by 4 bytes, later code by 8 (code alignment tuning)
# speedup vs baseline: 1.0015x; 1.0015x over previous
.LBB0_905:
	s_or_b64 exec, exec, s[24:25]
	v_ashrrev_i32_e32 v3, 9, v4
	v_mul_i32_i24_e32 v197, 0x2200, v3
	v_lshlrev_b32_e32 v3, 4, v2
	v_add_u32_e32 v6, 0x100, v2
	v_bfe_u32 v5, v4, 3, 6
	v_and_b32_e32 v150, 0x70, v3
	v_ashrrev_i32_e32 v3, 9, v6
	s_waitcnt vmcnt(2)
	v_add_u32_e32 v8, 0x280, v2
	v_mul_u32_u24_e32 v198, 0x88, v5
	v_bfe_u32 v5, v6, 3, 6
	v_mul_i32_i24_e32 v199, 0x2200, v3
	v_ashrrev_i32_e32 v3, 9, v8
	v_add_u32_e32 v10, 0x400, v2
	v_mul_u32_u24_e32 v200, 0x88, v5
	v_bfe_u32 v5, v8, 3, 6
	v_mul_i32_i24_e32 v201, 0x2200, v3
	v_ashrrev_i32_e32 v3, 9, v10
	v_add_u32_e32 v12, 0x580, v2
	v_mul_u32_u24_e32 v202, 0x88, v5
	v_bfe_u32 v5, v2, 3, 6
	v_mul_i32_i24_e32 v203, 0x2200, v3
	v_ashrrev_i32_e32 v3, 9, v12
	v_add_u32_e32 v14, 0x700, v2
	v_mul_u32_u24_e32 v204, 0x88, v5
	v_mul_i32_i24_e32 v205, 0x2200, v3
	v_ashrrev_i32_e32 v3, 9, v14
	v_bfe_u32 v5, v14, 3, 6
	s_waitcnt vmcnt(1)
	v_add_u32_e32 v16, 0x880, v2
	v_mul_i32_i24_e32 v206, 0x2200, v3
	v_mul_u32_u24_e32 v207, 0x88, v5
	v_ashrrev_i32_e32 v3, 9, v16
	v_bfe_u32 v5, v16, 3, 6
	v_ashrrev_i32_e32 v18, 3, v4
	s_waitcnt vmcnt(0)
	v_ashrrev_i32_e32 v20, 3, v6
	v_mul_i32_i24_e32 v208, 0x2200, v3
	v_mul_u32_u24_e32 v209, 0x88, v5
	v_ashrrev_i32_e32 v5, 31, v4
	s_lshl_b64 s[20:21], s[2:3], 11
	v_ashrrev_i32_e32 v19, 31, v18
	v_ashrrev_i32_e32 v21, 31, v20
	v_lshlrev_b32_e32 v3, 2, v2
	v_lshlrev_b64 v[152:153], 4, v[4:5]
	v_ashrrev_i32_e32 v7, 31, v6
	v_lshl_add_u64 v[170:171], s[20:21], 0, v[18:19]
	v_lshl_add_u64 v[172:173], s[20:21], 0, v[20:21]
	v_ashrrev_i32_e32 v148, 4, v4
	v_and_b32_e32 v3, 60, v3
	s_lshl_b64 s[20:21], s[2:3], 22
	v_and_b32_e32 v4, 31, v2
	v_readlane_b32 s2, v254, 27
	s_movk_i32 s24, 0x88
	v_lshlrev_b64 v[154:155], 4, v[6:7]
	v_bfe_u32 v6, v2, 5, 1
	v_lshl_or_b32 v1, v1, 5, v4
	v_mul_u32_u24_e32 v215, 0x88, v4
	v_lshlrev_b32_e32 v4, 2, v3
	v_mov_b32_e32 v5, v0
	v_readlane_b32 s3, v254, 28
	v_lshlrev_b32_e32 v212, 1, v3
	v_mul_lo_u32 v213, v1, s24
	v_lshlrev_b32_e32 v1, 2, v1
	v_lshl_add_u64 v[174:175], s[2:3], 0, v[4:5]
	global_load_dwordx4 v[240:243], v[174:175], off
	v_mul_u32_u24_e32 v3, 0x410, v6
	v_readlane_b32 s2, v253, 24
	v_mov_b32_e32 v151, v0
	s_movk_i32 s4, 0xa80
	v_add3_u32 v216, s2, v1, v3
	s_lshl_b32 s2, s30, 7
	s_add_u32 s2, s58, s2
	s_addc_u32 s3, s59, 0
	v_lshl_add_u64 v[178:179], s[2:3], 0, v[150:151]
	s_movk_i32 s2, 0x104
	v_mul_lo_u32 v1, v148, s2
	s_lshl_b32 s2, s31, 7
	v_readlane_b32 s18, v253, 57
	s_and_b32 s30, s2, 0x180
	v_cmp_gt_i32_e32 vcc, s4, v2
	s_movk_i32 s4, 0x900
	s_movk_i32 s6, 0x780
	s_movk_i32 s8, 0x600
	s_movk_i32 s12, 0x300
	s_movk_i32 s14, 0x180
	s_movk_i32 s16, 0x280
	v_readlane_b32 s19, v253, 58
	s_or_b32 s2, s20, s30
	v_cmp_gt_i32_e64 s[4:5], s4, v2
	v_cmp_gt_i32_e64 s[6:7], s6, v2
	v_cmp_gt_i32_e64 s[8:9], s8, v2
	v_cmp_gt_i32_e64 s[10:11], s38, v2
	v_cmp_gt_i32_e64 s[12:13], s12, v2
	v_cmp_gt_i32_e64 s[14:15], s14, v2
	v_cmp_gt_i32_e64 s[16:17], s16, v2
	v_cmp_gt_i32_e64 s[18:19], s18, v2
	v_ashrrev_i32_e32 v15, 31, v14
	v_and_b32_e32 v2, 15, v2
	s_add_u32 s2, s62, s2
	v_ashrrev_i32_e32 v9, 31, v8
	v_ashrrev_i32_e32 v11, 31, v10
	v_ashrrev_i32_e32 v13, 31, v12
	v_lshlrev_b64 v[166:167], 4, v[14:15]
	v_ashrrev_i32_e32 v17, 31, v16
	v_lshlrev_b32_e32 v176, 3, v2
	v_mov_b32_e32 v177, v0
	s_addc_u32 s3, s63, s21
	v_mov_b32_e32 v14, v0
	v_mov_b32_e32 v15, v0
	v_mul_lo_u32 v210, v18, s24
	v_mul_lo_u32 v211, v20, s24
	v_lshlrev_b64 v[156:157], 4, v[8:9]
	v_lshlrev_b64 v[158:159], 4, v[10:11]
	v_lshlrev_b64 v[160:161], 4, v[12:13]
	v_lshlrev_b64 v[168:169], 4, v[16:17]
	v_lshlrev_b32_e32 v214, 3, v6
	v_lshl_add_u32 v151, v2, 4, v1
	v_lshl_add_u64 v[180:181], s[2:3], 0, v[176:177]
	v_mul_lo_u32 v217, v148, s24
	s_mov_b32 s2, 0x1d600
	v_mov_b32_e32 v1, v0
	v_mov_b32_e32 v2, v0
	v_mov_b32_e32 v3, v0
	v_mov_b32_e32 v4, v0
	v_mov_b32_e32 v6, v0
	v_mov_b32_e32 v7, v0
	v_mov_b32_e32 v8, v0
	v_mov_b32_e32 v9, v0
	v_mov_b32_e32 v10, v0
	v_mov_b32_e32 v11, v0
	v_mov_b32_e32 v12, v0
	v_mov_b32_e32 v13, v0
	v_mov_b64_e32 v[30:31], v[14:15]
	v_mov_b64_e32 v[46:47], v[14:15]
	v_ashrrev_i32_e32 v149, 31, v148
	v_add3_u32 v218, v217, v212, s2
	s_mov_b32 s31, 0
	s_movk_i32 s24, 0xffc0
	s_movk_i32 s34, 0xff
	v_mov_b64_e32 v[28:29], v[12:13]
	v_mov_b64_e32 v[26:27], v[10:11]
	v_mov_b64_e32 v[24:25], v[8:9]
	v_mov_b64_e32 v[22:23], v[6:7]
	v_mov_b64_e32 v[20:21], v[4:5]
	v_mov_b64_e32 v[18:19], v[2:3]
	v_mov_b64_e32 v[16:17], v[0:1]
	v_mov_b64_e32 v[44:45], v[12:13]
	v_mov_b64_e32 v[42:43], v[10:11]
	v_mov_b64_e32 v[40:41], v[8:9]
	v_mov_b64_e32 v[38:39], v[6:7]
	v_mov_b64_e32 v[36:37], v[4:5]
	v_mov_b64_e32 v[34:35], v[2:3]
	v_mov_b64_e32 v[32:33], v[0:1]
	s_waitcnt lgkmcnt(0)
	s_waitcnt vmcnt(0)
	s_barrier
	s_branch .LBB0_907
	s_nop 0

.LBB0_939:
	s_andn2_saveexec_b64 s[2:3], s[26:27]
	s_cbranch_execz .LBB0_906
	s_and_b32 s25, s31, 1
	s_mul_i32 s26, s25, 0xaa00
	s_add_i32 s26, s26, 0
	v_add3_u32 v1, s26, v213, v214
	v_add_u32_e32 v1, 0x8800, v1
	ds_read2_b64 v[6:9], v1 offset1:2
	v_add3_u32 v15, s26, v215, v214
	ds_read2_b64 v[10:13], v1 offset0:4 offset1:6
	v_cvt_pk_bf16_f32 v2, v16, v17
	v_cvt_pk_bf16_f32 v3, v18, v19
	s_waitcnt lgkmcnt(1)
	v_lshlrev_b32_e32 v80, 16, v6
	v_and_b32_e32 v81, 0xffff0000, v6
	v_lshlrev_b32_e32 v82, 16, v7
	v_and_b32_e32 v83, 0xffff0000, v7
	v_lshlrev_b32_e32 v84, 16, v8
	v_and_b32_e32 v85, 0xffff0000, v8
	v_lshlrev_b32_e32 v86, 16, v9
	v_and_b32_e32 v87, 0xffff0000, v9
	ds_read2_b64 v[6:9], v15 offset1:2
	v_cvt_pk_bf16_f32 v4, v20, v21
	v_cvt_pk_bf16_f32 v5, v22, v23
	s_waitcnt lgkmcnt(1)
	v_lshlrev_b32_e32 v88, 16, v10
	v_and_b32_e32 v89, 0xffff0000, v10
	v_lshlrev_b32_e32 v90, 16, v11
	v_and_b32_e32 v91, 0xffff0000, v11
	v_lshlrev_b32_e32 v92, 16, v12
	v_and_b32_e32 v93, 0xffff0000, v12
	v_lshlrev_b32_e32 v94, 16, v13
	v_and_b32_e32 v95, 0xffff0000, v13
	v_add_u32_e32 v14, 0x2000, v15
	v_cvt_pk_bf16_f32 v10, v24, v25
	ds_read2_b64 v[228:231], v14 offset0:64 offset1:66
	s_waitcnt lgkmcnt(1)
	v_mfma_f32_32x32x16_bf16 v[80:95], v[6:9], v[2:5], v[80:95]
	v_cvt_pk_bf16_f32 v11, v26, v27
	v_cvt_pk_bf16_f32 v12, v28, v29
	v_cvt_pk_bf16_f32 v13, v30, v31
	v_cvt_pk_bf16_f32 v220, v32, v33
	v_cvt_pk_bf16_f32 v221, v34, v35
	v_cvt_pk_bf16_f32 v222, v36, v37
	ds_read2_b64 v[6:9], v15 offset0:4 offset1:6
	s_waitcnt lgkmcnt(1)
	v_mfma_f32_32x32x16_bf16 v[48:63], v[228:231], v[2:5], 0
	v_cvt_pk_bf16_f32 v223, v38, v39
	v_cvt_pk_bf16_f32 v224, v40, v41
	v_cvt_pk_bf16_f32 v225, v42, v43
	v_cvt_pk_bf16_f32 v226, v44, v45
	v_cvt_pk_bf16_f32 v227, v46, v47
	s_lshl_b32 s26, s31, 2
	ds_read2_b64 v[228:231], v14 offset0:68 offset1:70
	s_waitcnt lgkmcnt(1)
	v_mfma_f32_32x32x16_bf16 v[80:95], v[6:9], v[10:13], v[80:95]
	s_add_i32 s26, s26, 0
	s_add_i32 s26, s26, 0x23c00
	s_mulk_i32 s25, 0x4100
	ds_read2_b64 v[6:9], v15 offset0:8 offset1:10
	s_waitcnt lgkmcnt(1)
	v_mfma_f32_32x32x16_bf16 v[48:63], v[228:231], v[10:13], v[48:63]
	ds_read2_b64 v[228:231], v14 offset0:72 offset1:74
	s_waitcnt lgkmcnt(1)
	v_mfma_f32_32x32x16_bf16 v[80:95], v[6:9], v[220:223], v[80:95]
	ds_read2_b64 v[6:9], v15 offset0:12 offset1:14
	s_waitcnt lgkmcnt(1)
	v_mfma_f32_32x32x16_bf16 v[48:63], v[228:231], v[220:223], v[48:63]
	ds_read2_b64 v[228:231], v14 offset0:76 offset1:78
	s_waitcnt lgkmcnt(1)
	v_mfma_f32_32x32x16_bf16 v[80:95], v[6:9], v[224:227], v[80:95]
	ds_read2_b64 v[64:67], v1 offset0:8 offset1:10
	v_add_u32_e32 v14, 0x3000, v15
	s_waitcnt lgkmcnt(0)
	v_lshlrev_b32_e32 v96, 16, v64
	v_and_b32_e32 v97, 0xffff0000, v64
	v_mfma_f32_32x32x16_bf16 v[48:63], v[228:231], v[224:227], v[48:63]
	ds_read2_b64 v[6:9], v1 offset0:12 offset1:14
	v_add_u32_e32 v1, 0x1000, v15
	v_lshlrev_b32_e32 v98, 16, v65
	v_and_b32_e32 v99, 0xffff0000, v65
	v_lshlrev_b32_e32 v100, 16, v66
	v_and_b32_e32 v101, 0xffff0000, v66
	v_lshlrev_b32_e32 v102, 16, v67
	v_and_b32_e32 v103, 0xffff0000, v67
	ds_read2_b64 v[64:67], v1 offset0:32 offset1:34
	s_waitcnt lgkmcnt(1)
	v_lshlrev_b32_e32 v104, 16, v6
	v_and_b32_e32 v105, 0xffff0000, v6
	v_lshlrev_b32_e32 v106, 16, v7
	v_and_b32_e32 v107, 0xffff0000, v7
	v_lshlrev_b32_e32 v108, 16, v8
	v_and_b32_e32 v109, 0xffff0000, v8
	v_lshlrev_b32_e32 v110, 16, v9
	v_and_b32_e32 v111, 0xffff0000, v9
	ds_read2_b64 v[6:9], v14 offset0:96 offset1:98
	s_waitcnt lgkmcnt(1)
	v_mfma_f32_32x32x16_bf16 v[96:111], v[64:67], v[2:5], v[96:111]
	s_waitcnt lgkmcnt(0)
	v_mfma_f32_32x32x16_bf16 v[64:79], v[6:9], v[2:5], 0
	ds_read2_b64 v[2:5], v1 offset0:36 offset1:38
	v_cvt_pk_bf16_f32 v6, v80, v81
	v_cvt_pk_bf16_f32 v7, v82, v83
	v_cvt_pk_bf16_f32 v8, v84, v85
	v_cvt_pk_bf16_f32 v9, v86, v87
	ds_read2_b64 v[228:231], v14 offset0:100 offset1:102
	s_waitcnt lgkmcnt(1)
	v_mfma_f32_32x32x16_bf16 v[96:111], v[2:5], v[10:13], v[96:111]
	ds_read2_b64 v[2:5], v1 offset0:40 offset1:42
	s_waitcnt lgkmcnt(1)
	v_mfma_f32_32x32x16_bf16 v[64:79], v[228:231], v[10:13], v[64:79]
	v_cvt_pk_bf16_f32 v10, v88, v89
	v_cvt_pk_bf16_f32 v11, v90, v91
	v_cvt_pk_bf16_f32 v12, v92, v93
	v_cvt_pk_bf16_f32 v13, v94, v95
	ds_read2_b64 v[228:231], v14 offset0:104 offset1:106
	s_waitcnt lgkmcnt(1)
	v_mfma_f32_32x32x16_bf16 v[96:111], v[2:5], v[220:223], v[96:111]
	ds_read2_b64 v[2:5], v1 offset0:44 offset1:46
	s_waitcnt lgkmcnt(1)
	v_mfma_f32_32x32x16_bf16 v[64:79], v[228:231], v[220:223], v[64:79]
	v_add_u32_e32 v1, 0x4000, v15
	ds_read2_b64 v[228:231], v14 offset0:108 offset1:110
	s_waitcnt lgkmcnt(1)
	v_mfma_f32_32x32x16_bf16 v[96:111], v[2:5], v[224:227], v[96:111]
	ds_read2_b64 v[2:5], v1 offset0:128 offset1:130
	s_waitcnt lgkmcnt(1)
	v_mfma_f32_32x32x16_bf16 v[64:79], v[228:231], v[224:227], v[64:79]
	ds_read2_b64 v[228:231], v1 offset0:132 offset1:134
	s_waitcnt lgkmcnt(1)
	v_mfma_f32_32x32x16_bf16 v[48:63], v[2:5], v[6:9], v[48:63]
	v_add_u32_e32 v1, 0x5000, v15
	ds_read2_b64 v[2:5], v1 offset0:160 offset1:162
	s_waitcnt lgkmcnt(1)
	v_mfma_f32_32x32x16_bf16 v[48:63], v[228:231], v[10:13], v[48:63]
	ds_read2_b64 v[228:231], v1 offset0:164 offset1:166
	s_waitcnt lgkmcnt(1)
	v_mfma_f32_32x32x16_bf16 v[64:79], v[2:5], v[6:9], v[64:79]
	ds_read2_b64 v[80:83], v1 offset0:168 offset1:170
	ds_read2_b64 v[84:87], v1 offset0:172 offset1:174
	v_mov_b32_e32 v1, s26
	ds_read_b32 v14, v1
	v_add_u32_e32 v1, 0x6000, v15
	s_waitcnt lgkmcnt(0)
	v_pk_mul_f32 v[30:31], v[30:31], v[14:15] op_sel_hi:[1,0]
	v_mfma_f32_32x32x16_bf16 v[64:79], v[228:231], v[10:13], v[64:79]
	v_cvt_pk_bf16_f32 v2, v96, v97
	v_cvt_pk_bf16_f32 v3, v98, v99
	v_cvt_pk_bf16_f32 v4, v100, v101
	v_cvt_pk_bf16_f32 v5, v102, v103
	v_mul_f32_e64 v28, v28, v14
	v_mul_f32_e64 v29, v29, v14
	v_pk_mul_f32 v[26:27], v[26:27], v[14:15] op_sel_hi:[1,0]
	v_pk_mul_f32 v[24:25], v[24:25], v[14:15] op_sel_hi:[1,0]
	v_mfma_f32_32x32x16_bf16 v[64:79], v[80:83], v[2:5], v[64:79]
	v_cvt_pk_bf16_f32 v80, v104, v105
	v_cvt_pk_bf16_f32 v81, v106, v107
	v_cvt_pk_bf16_f32 v82, v108, v109
	v_cvt_pk_bf16_f32 v83, v110, v111
	v_mul_f32_e64 v22, v22, v14
	v_mul_f32_e64 v23, v23, v14
	v_pk_mul_f32 v[20:21], v[20:21], v[14:15] op_sel_hi:[1,0]
	v_pk_mul_f32 v[18:19], v[18:19], v[14:15] op_sel_hi:[1,0]
	v_mfma_f32_32x32x16_bf16 v[64:79], v[84:87], v[80:83], v[64:79]
	ds_read2_b64 v[84:87], v1 offset0:192 offset1:194
	v_mul_f32_e64 v16, v16, v14
	v_mul_f32_e64 v17, v17, v14
	v_mul_f32_e64 v46, v46, v14
	v_mul_f32_e64 v47, v47, v14
	v_pk_mul_f32 v[44:45], v[44:45], v[14:15] op_sel_hi:[1,0]
	v_pk_mul_f32 v[42:43], v[42:43], v[14:15] op_sel_hi:[1,0]
	v_pk_mul_f32 v[40:41], v[40:41], v[14:15] op_sel_hi:[1,0]
	v_pk_mul_f32 v[38:39], v[38:39], v[14:15] op_sel_hi:[1,0]
	ds_read2_b64 v[228:231], v1 offset0:196 offset1:198
	s_waitcnt lgkmcnt(1)
	v_mfma_f32_32x32x16_bf16 v[16:31], v[84:87], v[6:9], v[16:31]
	v_mul_f32_e64 v36, v36, v14
	v_mul_f32_e64 v37, v37, v14
	v_mul_f32_e64 v34, v34, v14
	v_mul_f32_e64 v35, v35, v14
	v_pk_mul_f32 v[32:33], v[32:33], v[14:15] op_sel_hi:[1,0]
	s_waitcnt lgkmcnt(0)
	v_mfma_f32_32x32x16_bf16 v[16:31], v[228:231], v[10:13], v[16:31]
	ds_read2_b64 v[84:87], v1 offset0:200 offset1:202
	ds_read2_b64 v[88:91], v1 offset0:204 offset1:206
	v_add_u32_e32 v1, 0x7000, v15
	s_waitcnt lgkmcnt(1)
	v_mfma_f32_32x32x16_bf16 v[16:31], v[84:87], v[2:5], v[16:31]
	ds_read2_b64 v[84:87], v1 offset0:224 offset1:226
	s_waitcnt lgkmcnt(0)
	v_mfma_f32_32x32x16_bf16 v[32:47], v[84:87], v[6:9], v[32:47]
	v_mfma_f32_32x32x16_bf16 v[16:31], v[88:91], v[80:83], v[16:31]
	ds_read2_b64 v[88:91], v1 offset0:228 offset1:230
	ds_read2_b64 v[92:95], v1 offset0:232 offset1:234
	ds_read2_b64 v[96:99], v1 offset0:236 offset1:238
	v_add_u32_e32 v1, s25, v216
	v_add_u32_e32 v6, 0x800, v1
	ds_write2_b32 v1, v48, v49 offset1:65
	ds_write2_b32 v1, v50, v51 offset0:130 offset1:195
	ds_write2_b32 v6, v52, v53 offset0:8 offset1:73
	ds_write2_b32 v6, v54, v55 offset0:138 offset1:203
	v_add_u32_e32 v6, 0x1000, v1
	s_waitcnt lgkmcnt(6)
	v_mfma_f32_32x32x16_bf16 v[32:47], v[88:91], v[10:13], v[32:47]
	ds_write2_b32 v6, v56, v57 offset0:16 offset1:81
	ds_write2_b32 v6, v58, v59 offset0:146 offset1:211
	v_add_u32_e32 v6, 0x1800, v1
	ds_write2_b32 v6, v60, v61 offset0:24 offset1:89
	ds_write2_b32 v6, v62, v63 offset0:154 offset1:219
	v_add_u32_e32 v6, 0x2000, v1
	ds_write2_b32 v6, v64, v65 offset0:32 offset1:97
	ds_write2_b32 v6, v66, v67 offset0:162 offset1:227
	v_add_u32_e32 v6, 0x2800, v1
	ds_write2_b32 v6, v68, v69 offset0:40 offset1:105
	ds_write2_b32 v6, v70, v71 offset0:170 offset1:235
	s_waitcnt lgkmcnt(13)
	v_mfma_f32_32x32x16_bf16 v[32:47], v[92:95], v[2:5], v[32:47]
	v_add_u32_e32 v2, 0x3000, v1
	v_add_u32_e32 v1, 0x3800, v1
	ds_write2_b32 v2, v72, v73 offset0:48 offset1:113
	ds_write2_b32 v2, v74, v75 offset0:178 offset1:243
	ds_write2_b32 v1, v76, v77 offset0:56 offset1:121
	ds_write2_b32 v1, v78, v79 offset0:186 offset1:251
	s_waitcnt lgkmcnt(14)
	v_mfma_f32_32x32x16_bf16 v[32:47], v[96:99], v[80:83], v[32:47]
	s_branch .LBB0_906
	s_nop 0
